# GEMM phase prologues de-serialised: rstd loads overlap tile DMA, K-tile-1 loads issued before waiting on K-tile 0
# speedup vs baseline: 1.0051x; 1.0014x over previous
; #define PG8_STAGE(bufoff, gbase, voff) do { _Pragma("unroll") for (int _i = 0; _i < 2; ++_i) \
;         __builtin_amdgcn_global_load_lds((const unsigned*)((const char*)(gbase) + (voff)[_i]), (PG8_LAS unsigned*)(lds + (bufoff) + ldsw + _i * 8192), 16, 0, 0); } while (0)
; #define PG8_WAIT_V(n) asm volatile("s_waitcnt vmcnt(" #n ")" ::: "memory")
; #define PG8_BAR __builtin_amdgcn_s_barrier()
; template <class Epi, class Sched, bool ALIGN_EPI = false, bool SP2 = false>
; __device__ __forceinline__ void gemm_phase(PG8_LAS unsigned char* lds, const Gemm g, const Sched& S, const Epi& E) {
;     ...
;         PG8_STAGE(PG8_SB(0, 0), cB, voffB); PG8_STAGE(PG8_SB(0, 1), cB + hstep, voffB); PG8_STAGE(PG8_SA(0, 0), cA, voffA); PG8_STAGE(PG8_SA(0, 1), cA + hstep, voffA);
;         if (wr == 1) PG8_BAR;
;         PG8_WAIT_V(2); PG8_BAR;
;         PG8_STAGE(PG8_SB(1, 0), cB + kstep, voffB); PG8_STAGE(PG8_SA(1, 0), cA + kstep, voffA); PG8_STAGE(PG8_SB(1, 1), cB + hstep + kstep, voffB);
;         PG8_WAIT_V(6); PG8_BAR;
.LBB0_118:
	v_and_b32_e32 v15, 15, v9
	v_lshrrev_b32_e32 v9, 1, v9
	v_and_b32_e32 v9, 24, v9
	v_lshlrev_b32_e32 v16, 1, v9
	v_lshl_or_b32 v158, s34, 6, v15
	v_lshl_or_b32 v16, v15, 6, v16
	v_lshlrev_b32_e32 v15, 2, v15
	s_sext_i32_i8 s64, s31
	s_lshl_b32 s31, s34, 13
	v_and_b32_e32 v17, 32, v15
	v_bitop3_b32 v18, v16, s31, v17 bitop3:0xde
	s_lshl_b32 s31, s35, 5
	s_and_b32 s42, s31, 0x60
	s_add_i32 m0, s37, 0x18000
	v_lshl_add_u64 v[6:7], v[6:7], 0, s[14:15]
	s_lshl_b32 s31, s42, 7
	global_load_lds_dwordx4 v[6:7], off
	v_lshl_add_u64 v[4:5], v[4:5], 0, s[14:15]
	s_add_i32 m0, s37, 0x1a000
	s_add_i32 s60, s37, 0x8000
	s_add_i32 s61, s37, 0xa000
	global_load_lds_dwordx4 v[4:5], off
	v_lshl_add_u64 v[0:1], v[0:1], 0, s[14:15]
	s_mov_b32 m0, s60
	s_add_u32 s34, s4, 0x40080
	global_load_lds_dwordx4 v[0:1], off
	v_lshl_add_u64 v[0:1], v[2:3], 0, s[14:15]
	s_mov_b32 m0, s61
	s_addc_u32 s35, s5, 0
	global_load_lds_dwordx4 v[0:1], off
	s_add_i32 m0, s37, 0x1c000
	v_lshl_add_u64 v[0:1], s[34:35], 0, v[138:139]
	global_load_lds_dwordx4 v[0:1], off
	v_lshl_add_u64 v[0:1], s[34:35], 0, v[142:143]
	s_add_i32 m0, s37, 0x1e000
	v_bitop3_b32 v159, v16, s31, v17 bitop3:0xde
	global_load_lds_dwordx4 v[0:1], off
	s_waitcnt vmcnt(8)
	s_barrier
	v_lshlrev_b32_e32 v0, 14, v8
	s_add_i32 s31, 0, 0x20000
	v_and_b32_e32 v0, 0xffff8000, v0
	s_cmpk_lt_u32 s30, 0x100
	v_lshl_add_u32 v0, v10, 11, v0
	v_and_b32_e32 v1, 1, v8
	s_cselect_b64 s[44:45], -1, 0
	s_and_b32 s30, s30, 0xffffff00
	v_lshl_or_b32 v0, v1, 6, v0
	v_lshl_add_u32 v160, v156, 2, s31
	s_add_i32 s31, s31, s30
	v_lshl_add_u32 v146, v11, 1, v0
	v_lshlrev_b32_e32 v0, 14, v12
	v_add_u32_e32 v161, s31, v15
	v_readlane_b32 s30, v253, 52
	v_and_b32_e32 v0, 0xffff8000, v0
	s_waitcnt vmcnt(6)
	v_readlane_b32 s31, v253, 53
	v_lshl_add_u32 v0, v13, 11, v0
	v_and_b32_e32 v1, 1, v12
	v_lshl_add_u64 v[144:145], s[30:31], 0, v[176:177]
	s_and_b64 s[30:31], s[38:39], exec
	v_lshl_or_b32 v0, v1, 6, v0
	s_cselect_b32 s62, 25, 22
	s_mov_b32 s65, 0
	v_or_b32_e32 v162, s42, v9
	v_mov_b32_e32 v147, v177
	v_lshl_add_u32 v148, v14, 1, v0
	v_mov_b32_e32 v149, v177
	v_add_u32_e32 v163, 0, v18
	s_barrier
	s_branch .LBB0_121

; #define PG8_STAGE(bufoff, gbase, voff) do { _Pragma("unroll") for (int _i = 0; _i < 2; ++_i) \
;         __builtin_amdgcn_global_load_lds((const unsigned*)((const char*)(gbase) + (voff)[_i]), (PG8_LAS unsigned*)(lds + (bufoff) + ldsw + _i * 8192), 16, 0, 0); } while (0)
; #define PG8_WAIT_V(n) asm volatile("s_waitcnt vmcnt(" #n ")" ::: "memory")
; #define PG8_BAR __builtin_amdgcn_s_barrier()
; template <class Epi, class Sched, bool ALIGN_EPI = false, bool SP2 = false>
; __device__ __forceinline__ void gemm_phase(PG8_LAS unsigned char* lds, const Gemm g, const Sched& S, const Epi& E) {
;     ...
;         PG8_STAGE(PG8_SB(0, 0), cB, voffB); PG8_STAGE(PG8_SB(0, 1), cB + hstep, voffB); PG8_STAGE(PG8_SA(0, 0), cA, voffA); PG8_STAGE(PG8_SA(0, 1), cA + hstep, voffA);
;         if (wr == 1) PG8_BAR;
;         PG8_WAIT_V(2); PG8_BAR;
;         PG8_STAGE(PG8_SB(1, 0), cB + kstep, voffB); PG8_STAGE(PG8_SA(1, 0), cA + kstep, voffA); PG8_STAGE(PG8_SB(1, 1), cB + hstep + kstep, voffB);
;         PG8_WAIT_V(6); PG8_BAR;
.LBB0_146:
	v_and_b32_e32 v1, 15, v10
	v_lshrrev_b32_e32 v10, 1, v10
	v_and_b32_e32 v10, 24, v10
	v_lshlrev_b32_e32 v17, 1, v10
	v_lshl_or_b32 v188, s34, 6, v1
	v_lshl_or_b32 v17, v1, 6, v17
	v_lshlrev_b32_e32 v1, 2, v1
	s_sext_i32_i8 s63, s31
	s_lshl_b32 s31, s34, 13
	v_and_b32_e32 v18, 32, v1
	v_bitop3_b32 v19, v17, s31, v18 bitop3:0xde
	s_lshl_b32 s31, s35, 5
	s_and_b32 s31, s31, 0x60
	s_add_i32 m0, s37, 0x18000
	v_lshl_add_u64 v[8:9], v[8:9], 0, s[14:15]
	s_lshl_b32 s34, s31, 7
	global_load_lds_dwordx4 v[8:9], off
	v_lshl_add_u64 v[6:7], v[6:7], 0, s[14:15]
	s_add_i32 m0, s37, 0x1a000
	s_add_i32 s60, s37, 0x8000
	s_add_i32 s61, s37, 0xa000
	v_bitop3_b32 v189, v17, s34, v18 bitop3:0xde
	global_load_lds_dwordx4 v[6:7], off
	v_lshl_add_u64 v[2:3], v[2:3], 0, s[14:15]
	s_mov_b32 m0, s60
	s_add_u32 s34, s4, 0x40080
	global_load_lds_dwordx4 v[2:3], off
	v_lshl_add_u64 v[2:3], v[4:5], 0, s[14:15]
	s_mov_b32 m0, s61
	s_addc_u32 s35, s5, 0
	global_load_lds_dwordx4 v[2:3], off
	s_add_i32 m0, s37, 0x1c000
	v_lshl_add_u64 v[2:3], s[34:35], 0, v[176:177]
	global_load_lds_dwordx4 v[2:3], off
	v_lshl_add_u64 v[2:3], s[34:35], 0, v[156:157]
	s_add_i32 m0, s37, 0x1e000
	s_add_i32 s34, 0, 0x20000
	global_load_lds_dwordx4 v[2:3], off
	s_waitcnt vmcnt(8)
	s_barrier
	s_cmpk_lt_u32 s30, 0x100
	s_cselect_b64 s[44:45], -1, 0
	s_and_b32 s30, s30, 0xffffff00
	v_lshl_add_u32 v190, v186, 2, s34
	s_add_i32 s34, s34, s30
	v_add_u32_e32 v191, s34, v1
	v_readlane_b32 s34, v253, 54
	v_mov_b32_e32 v1, v177
	v_readlane_b32 s35, v253, 55
	s_waitcnt vmcnt(6)
	v_or_b32_e32 v192, s31, v10
	v_mov_b32_e32 v161, v177
	v_lshl_add_u64 v[158:159], s[34:35], 0, v[0:1]
	v_lshlrev_b32_e32 v0, 14, v11
	v_and_b32_e32 v0, 0xffff8000, v0
	v_lshl_add_u32 v0, v12, 11, v0
	v_and_b32_e32 v1, 1, v11
	v_lshl_or_b32 v0, v1, 6, v0
	v_lshl_add_u32 v160, v13, 1, v0
	v_lshlrev_b32_e32 v0, 14, v14
	v_and_b32_e32 v0, 0xffff8000, v0
	v_lshl_add_u32 v0, v15, 11, v0
	v_and_b32_e32 v1, 1, v14
	v_lshl_or_b32 v0, v1, 6, v0
	v_lshl_add_u32 v162, v16, 1, v0
	v_mov_b32_e32 v163, v177
	s_mov_b32 s64, 0
	v_add_u32_e32 v193, 0, v19
	s_barrier
	s_branch .LBB0_149

; #define PG8_STAGE(bufoff, gbase, voff) do { _Pragma("unroll") for (int _i = 0; _i < 2; ++_i) \
;         __builtin_amdgcn_global_load_lds((const unsigned*)((const char*)(gbase) + (voff)[_i]), (PG8_LAS unsigned*)(lds + (bufoff) + ldsw + _i * 8192), 16, 0, 0); } while (0)
; #define PG8_WAIT_V(n) asm volatile("s_waitcnt vmcnt(" #n ")" ::: "memory")
; #define PG8_BAR __builtin_amdgcn_s_barrier()
; template <class Epi, class Sched, bool ALIGN_EPI = false, bool SP2 = false>
; __device__ __forceinline__ void gemm_phase(PG8_LAS unsigned char* lds, const Gemm g, const Sched& S, const Epi& E) {
;     ...
;         PG8_STAGE(PG8_SB(0, 0), cB, voffB); PG8_STAGE(PG8_SB(0, 1), cB + hstep, voffB); PG8_STAGE(PG8_SA(0, 0), cA, voffA); PG8_STAGE(PG8_SA(0, 1), cA + hstep, voffA);
;         if (wr == 1) PG8_BAR;
;         PG8_WAIT_V(2); PG8_BAR;
;         PG8_STAGE(PG8_SB(1, 0), cB + kstep, voffB); PG8_STAGE(PG8_SA(1, 0), cA + kstep, voffA); PG8_STAGE(PG8_SB(1, 1), cB + hstep + kstep, voffB);
;         PG8_WAIT_V(6); PG8_BAR;
.LBB0_179:
	s_lshl_b64 s[40:41], s[2:3], 21
	s_add_u32 s48, s88, s40
	s_addc_u32 s49, s89, s41
	s_add_i32 m0, s36, 0x18000
	v_lshl_add_u64 v[0:1], v[0:1], 0, s[14:15]
	global_load_lds_dwordx4 v[0:1], off
	v_lshl_add_u64 v[0:1], v[2:3], 0, s[14:15]
	s_add_i32 m0, s36, 0x1a000
	s_add_i32 s60, s36, 0x8000
	global_load_lds_dwordx4 v[0:1], off
	v_lshl_add_u64 v[0:1], v[8:9], 0, s[14:15]
	s_mov_b32 m0, s60
	s_add_i32 s61, s36, 0xa000
	global_load_lds_dwordx4 v[0:1], off
	v_lshl_add_u64 v[0:1], v[10:11], 0, s[14:15]
	s_mov_b32 m0, s61
	s_and_b32 s62, s31, 3
	global_load_lds_dwordx4 v[0:1], off
	s_add_i32 m0, s36, 0x1c000
	v_lshl_add_u64 v[0:1], v[4:5], 0, s[14:15]
	global_load_lds_dwordx4 v[0:1], off
	v_lshl_add_u64 v[0:1], v[6:7], 0, s[14:15]
	s_add_i32 m0, s36, 0x1e000
	s_lshr_b32 s63, s27, 6
	global_load_lds_dwordx4 v[0:1], off
	s_waitcnt vmcnt(8)
	s_barrier
	v_bfe_u32 v0, v12, 4, 2
	v_and_b32_e32 v1, 15, v12
	v_lshlrev_b32_e32 v3, 4, v0
	v_lshl_or_b32 v233, s38, 6, v1
	v_lshl_or_b32 v1, v1, 6, v3
	v_lshlrev_b32_e32 v3, 2, v12
	s_lshl_b32 s2, s38, 13
	v_and_b32_e32 v3, 32, v3
	v_lshlrev_b32_e32 v2, 3, v0
	v_bitop3_b32 v4, v1, s2, v3 bitop3:0xde
	s_lshl_b32 s2, s62, 12
	s_add_i32 s64, s63, -2
	v_cmp_eq_u32_e64 s[38:39], 0, v0
	v_add_u32_e32 v0, v15, v13
	v_bitop3_b32 v234, v1, s2, v3 bitop3:0xde
	s_cmpk_lt_u32 s30, 0x100
	v_add_lshl_u32 v0, v0, v14, 1
	v_mov_b32_e32 v1, v177
	s_waitcnt vmcnt(6)
	s_cselect_b64 s[50:51], -1, 0
	s_ashr_i32 s65, s19, 31
	v_lshl_add_u64 v[192:193], s[22:23], 0, v[0:1]
	v_add_u32_e32 v0, v18, v16
	s_cmp_lg_u64 s[44:45], 0
	v_add_lshl_u32 v0, v0, v17, 1
	v_lshl_or_b32 v235, s62, 5, v2
	s_mov_b32 s2, 0
	s_cselect_b64 s[52:53], -1, 0
	s_mov_b32 s27, s26
	v_lshl_add_u64 v[194:195], s[22:23], 0, v[0:1]
	v_add_u32_e32 v236, 0, v4
	s_barrier
	s_branch .LBB0_182

; #define PG8_STAGE(bufoff, gbase, voff) do { _Pragma("unroll") for (int _i = 0; _i < 2; ++_i) \
;         __builtin_amdgcn_global_load_lds((const unsigned*)((const char*)(gbase) + (voff)[_i]), (PG8_LAS unsigned*)(lds + (bufoff) + ldsw + _i * 8192), 16, 0, 0); } while (0)
; #define LAS __attribute__((address_space(3)))
;     __device__ __forceinline__ void rs_first(const Unit& u, LAS unsigned char* lds, int tid) const { f32x4 a, b; rs_issue(ssp, u, tid, a, b); rs_finish(lds, 0, tid, a, b); }
;     __device__ __forceinline__ void rs_first(const Unit& u, LAS unsigned char* lds, int tid) const { f32x4 a, b; rs_issue(ssp, u, tid, a, b); rs_finish(lds, 0, tid, a, b); }
;     __device__ __forceinline__ void rs_first(const Unit& u, LAS unsigned char* lds, int tid) const { f32x4 a, b; rs_issue(ssp, u, tid, a, b); rs_finish(lds, 0, tid, a, b); }
; template <class Epi, class Sched, bool ALIGN_EPI = false, bool SP2 = false>
; __device__ __forceinline__ void gemm_phase(PG8_LAS unsigned char* lds, const Gemm g, const Sched& S, const Epi& E) {
;     ...
;     const char* cA = (const char*)g.A + (size_t)cur.pm * tstep; const char* cB = (const char*)g.Bt + (size_t)cur.pn * tstep;
;     S.a_ready(cur);
;     E.rs_first(cur, lds, tid);
;     if constexpr (SP2) {
;         PG8_STAGE(PG8_SB(0, 0), cB, voffB); PG8_STAGE(PG8_SB(0, 1), cB + hstep, voffB); PG8_STAGE(PG8_SA(0, 0), cA, voffA); PG8_STAGE(PG8_SA(0, 1), cA + hstep, voffA);
; __device__ __forceinline__ void rs_finish(LAS unsigned char* lds, int buf, int tid, const f32x4& a, const f32x4& b) {
;     float t = ((a.x + a.y) + (a.z + a.w)) + ((b.x + b.y) + (b.z + b.w)); t += __shfl_xor(t, 1);
;     if (!(tid & 1)) ((LAS float*)(lds + RS_LDS_OFF))[buf * 256 + (tid >> 1)] = rsqrtf(t * (1.f / D) + RMS_EPS);
; }
.LBB0_224:
	s_and_b64 vcc, exec, s[64:65]
	s_cbranch_vccz .LBB0_247
	v_mov_b32_e32 v10, v218
	s_cmpk_gt_i32 s19, 0xaff
	v_readfirstlane_b32 s24, v10
	s_cbranch_scc1 .LBB0_247
	s_cmp_lg_u32 s18, 0
	s_cselect_b64 s[4:5], -1, 0
	s_and_b64 s[20:21], s[4:5], exec
	s_cselect_b32 s2, 2, 0
	v_readlane_b32 s20, v255, 21
	s_add_i32 s2, s2, s20
	s_lshl_b32 s2, s2, 19
	s_lshl_b64 s[20:21], s[2:3], 2
	s_add_u32 s22, s88, s20
	s_addc_u32 s23, s89, s21
	s_ashr_i32 s36, s19, 31
	s_lshr_b32 s2, s36, 29
	s_add_i32 s2, s19, s2
	s_ashr_i32 s20, s2, 3
	s_and_b32 s2, s2, -8
	s_sub_i32 s2, s19, s2
	s_cmp_lt_i32 s2, 0
	s_movk_i32 s21, 0x161
	s_cselect_b32 s21, s21, 0x160
	s_mul_i32 s2, s2, s21
	s_add_i32 s2, s2, s20
	s_mul_hi_i32 s20, s2, 0x2e8ba2e9
	s_lshr_b32 s21, s20, 31
	s_ashr_i32 s20, s20, 5
	s_add_i32 s20, s20, s21
	s_lshl_b32 s21, s20, 3
	s_mulk_i32 s20, 0xb0
	s_sub_i32 s2, s2, s20
	s_bfe_u32 s20, s2, 0x3001c
	s_add_i32 s20, s2, s20
	s_and_b32 s25, s20, 0xfff8
	s_sub_i32 s2, s2, s25
	s_sext_i32_i16 s2, s2
	s_add_i32 s28, s21, s2
	v_ashrrev_i32_e32 v158, 1, v10
	v_lshl_add_u32 v0, s28, 8, v158
	s_waitcnt lgkmcnt(0)
	v_ashrrev_i32_e32 v1, 31, v0
	v_lshlrev_b64 v[0:1], 6, v[0:1]
	v_lshl_add_u64 v[2:3], s[22:23], 0, v[0:1]
	v_lshlrev_b32_e32 v0, 3, v10
	v_and_b32_e32 v0, 8, v0
	v_lshlrev_b32_e32 v0, 2, v0
	v_mov_b32_e32 v1, v177
	v_lshl_add_u64 v[6:7], v[2:3], 0, v[0:1]
	global_load_dwordx4 v[100:103], v[6:7], off
	s_nop 0
	global_load_dwordx4 v[104:107], v[6:7], off offset:16
	v_cmp_lt_i32_e32 vcc, v226, v225
	s_sext_i32_i16 s2, s20
	s_lshr_b32 s25, s2, 3
	v_cndmask_b32_e32 v11, v224, v226, vcc
	v_lshlrev_b32_e32 v159, 2, v11
	v_ashrrev_i32_e32 v2, 31, v10
	v_lshrrev_b32_e32 v2, 26, v2
	v_add_u32_e32 v2, v10, v2
	v_cndmask_b32_e64 v1, 0, 1, s[4:5]
	v_ashrrev_i32_e32 v11, 6, v2
	v_bfe_i32 v2, v10, 27, 1
	v_readfirstlane_b32 s2, v1
	v_lshlrev_b32_e32 v1, 4, v10
	v_lshrrev_b32_e32 v2, 22, v2
	v_add_u32_e32 v2, v1, v2
	v_and_b32_e32 v2, 0xfffffc00, v2
	v_sub_u32_e32 v2, v1, v2
	v_lshrrev_b32_e32 v3, 4, v2
	v_bitop3_b32 v2, v3, v2, 32 bitop3:0x6c
	v_ashrrev_i32_e32 v4, 31, v2
	v_lshrrev_b32_e32 v4, 26, v4
	v_add_u32_e32 v4, v2, v4
	v_lshlrev_b32_e32 v3, 3, v11
	v_ashrrev_i32_e32 v12, 6, v4
	v_and_b32_e32 v4, 0xc0, v4
	v_and_b32_e32 v3, -16, v3
	v_sub_u32_e32 v2, v2, v4
	v_add_u32_e32 v3, v12, v3
	v_ashrrev_i16_sdwa v2, v223, sext(v2) dst_sel:DWORD dst_unused:UNUSED_PAD src0_sel:DWORD src1_sel:BYTE_0
	v_lshlrev_b32_e32 v5, 5, v11
	v_bfe_i32 v13, v2, 0, 16
	v_lshlrev_b32_e32 v2, 1, v3
	v_lshrrev_b32_e32 v4, 2, v3
	v_and_b32_e32 v6, 3, v12
	s_mov_b32 s20, 0x1fffe0
	v_and_b32_e32 v5, 32, v5
	v_and_b32_e32 v2, 24, v2
	v_and_b32_e32 v4, 4, v4
	v_and_or_b32 v6, v3, s20, v6
	v_or3_b32 v2, v6, v4, v2
	v_add_lshl_u32 v4, v5, v13, 1
	v_add_u32_e32 v1, 0x2000, v1
	v_lshl_add_u32 v176, v2, 11, v4
	v_ashrrev_i32_e32 v2, 31, v1
	v_readlane_b32 s4, v255, 14
	v_lshrrev_b32_e32 v2, 22, v2
	s_or_b32 s2, s4, s2
	v_add_u32_e32 v2, v1, v2
	s_mul_i32 s2, s2, 0x580000
	v_ashrrev_i32_e32 v14, 10, v2
	s_lshl_b64 s[4:5], s[2:3], 1
	v_readlane_b32 s2, v253, 34
	v_mul_i32_i24_e32 v2, 0x400, v14
	s_add_u32 s2, s2, s4
	v_readlane_b32 s4, v253, 35
	v_sub_u32_e32 v1, v1, v2
	s_addc_u32 s37, s4, s5
	s_ashr_i32 s29, s28, 31
	v_lshrrev_b32_e32 v2, 4, v1
	s_lshl_b64 s[4:5], s[28:29], 19
	v_bitop3_b32 v1, v2, v1, 32 bitop3:0x6c
	s_add_u32 s40, s82, s4
	s_sext_i32_i16 s30, s25
	v_lshl_add_u32 v136, v3, 11, v4
	v_ashrrev_i32_e32 v3, 31, v1
	s_addc_u32 s41, s83, s5
	s_ashr_i32 s31, s30, 31
	v_lshrrev_b32_e32 v3, 26, v3
	s_lshl_b64 s[4:5], s[30:31], 19
	v_add_u32_e32 v3, v1, v3
	s_add_u32 s4, s2, s4
	v_lshlrev_b32_e32 v2, 3, v14
	v_ashrrev_i32_e32 v15, 6, v3
	v_and_b32_e32 v3, 0xc0, v3
	s_addc_u32 s5, s37, s5
	v_and_b32_e32 v2, -16, v2
	v_sub_u32_e32 v1, v1, v3
	s_ashr_i32 s26, s24, 6
	v_add_u32_e32 v2, v15, v2
	v_ashrrev_i16_sdwa v1, v223, sext(v1) dst_sel:DWORD dst_unused:UNUSED_PAD src0_sel:DWORD src1_sel:BYTE_0
	s_lshl_b32 s29, s26, 10
	v_lshlrev_b32_e32 v4, 5, v14
	v_bfe_i32 v16, v1, 0, 16
	v_lshlrev_b32_e32 v1, 1, v2
	v_lshrrev_b32_e32 v3, 2, v2
	v_and_b32_e32 v5, 3, v15
	s_add_i32 s31, s29, 0
	v_and_b32_e32 v4, 32, v4
	v_and_b32_e32 v1, 24, v1
	v_and_b32_e32 v3, 4, v3
	v_and_or_b32 v5, v2, s20, v5
	s_add_i32 m0, s31, 0x10000
	s_ashr_i32 s25, s24, 8
	v_or3_b32 v1, v5, v3, v1
	v_add_lshl_u32 v3, v4, v16, 1
	global_load_lds_dwordx4 v176, s[4:5]
	s_add_i32 m0, s31, 0x12000
	v_lshl_add_u32 v140, v1, 11, v3
	s_add_u32 s20, s4, 0x40000
	global_load_lds_dwordx4 v140, s[4:5]
	s_addc_u32 s21, s5, 0
	s_add_i32 m0, s31, 0x14000
	s_add_i32 s52, s31, 0x2000
	global_load_lds_dwordx4 v176, s[20:21]
	s_add_i32 m0, s31, 0x16000
	v_lshl_add_u32 v138, v2, 11, v3
	global_load_lds_dwordx4 v140, s[20:21]
	s_mov_b32 m0, s31
	s_add_u32 s20, s40, 0x40000
	global_load_lds_dwordx4 v136, s[40:41]
	s_mov_b32 m0, s52
	s_addc_u32 s21, s41, 0
	s_add_i32 s53, s31, 0x4000
	global_load_lds_dwordx4 v138, s[40:41]
	s_mov_b32 m0, s53
	s_add_i32 s54, s31, 0x6000
	global_load_lds_dwordx4 v136, s[20:21]
	s_mov_b32 m0, s54
	v_mov_b32_e32 v141, v177
	global_load_lds_dwordx4 v138, s[20:21]
	s_waitcnt vmcnt(8)
	v_add_f32_e32 v108, v100, v101
	v_add_f32_e32 v109, v102, v103
	v_add_f32_e32 v110, v104, v105
	v_add_f32_e32 v111, v106, v107
	v_add_f32_e32 v108, v108, v109
	v_add_f32_e32 v109, v110, v111
	v_add_f32_e32 v108, v108, v109
	v_and_b32_e32 v110, 1, v10
	v_cmp_eq_u32_e64 s[38:39], 0, v110
	v_add_f32_dpp v108, v108, v108 quad_perm:[1,0,3,2] row_mask:0xf bank_mask:0xf
	s_and_saveexec_b64 s[20:21], s[38:39]
	v_fmamk_f32 v108, v108, 0x3a800000, v222
	v_mul_f32_e32 v109, 0x4b800000, v108
	v_cmp_gt_f32_e32 vcc, s7, v108
	s_nop 1
	v_cndmask_b32_e32 v108, v108, v109, vcc
	v_rsq_f32_e32 v108, v108
	v_lshl_add_u32 v109, v158, 2, 0
	v_add_u32_e32 v109, 0x20000, v109
	v_mul_f32_e32 v110, 0x45800000, v108
	v_cndmask_b32_e32 v108, v108, v110, vcc
	ds_write_b32 v109, v108
	s_or_b64 exec, exec, s[20:21]
	s_waitcnt lgkmcnt(0)
	v_mov_b32_e32 v137, v177
	v_mov_b32_e32 v139, v177
	s_cmp_eq_u32 s25, 1
	v_lshl_add_u64 v[8:9], s[4:5], 0, v[176:177]
	v_lshl_add_u64 v[6:7], s[4:5], 0, v[140:141]
	v_lshl_add_u64 v[2:3], s[40:41], 0, v[136:137]
	s_cselect_b64 s[20:21], -1, 0
	s_cmp_lg_u32 s25, 1
	v_lshl_add_u64 v[4:5], s[40:41], 0, v[138:139]
	s_cbranch_scc1 .LBB0_230
	s_barrier
; #define PG8_STAGE(bufoff, gbase, voff) do { _Pragma("unroll") for (int _i = 0; _i < 2; ++_i) \
;         __builtin_amdgcn_global_load_lds((const unsigned*)((const char*)(gbase) + (voff)[_i]), (PG8_LAS unsigned*)(lds + (bufoff) + ldsw + _i * 8192), 16, 0, 0); } while (0)
; #define PG8_WAIT_V(n) asm volatile("s_waitcnt vmcnt(" #n ")" ::: "memory")
; #define PG8_BAR __builtin_amdgcn_s_barrier()
; template <class Epi, class Sched, bool ALIGN_EPI = false, bool SP2 = false>
; __device__ __forceinline__ void gemm_phase(PG8_LAS unsigned char* lds, const Gemm g, const Sched& S, const Epi& E) {
;     ...
;         PG8_STAGE(PG8_SB(0, 0), cB, voffB); PG8_STAGE(PG8_SB(0, 1), cB + hstep, voffB); PG8_STAGE(PG8_SA(0, 0), cA, voffA); PG8_STAGE(PG8_SA(0, 1), cA + hstep, voffA);
;         if (wr == 1) PG8_BAR;
;         PG8_WAIT_V(2); PG8_BAR;
;         PG8_STAGE(PG8_SB(1, 0), cB + kstep, voffB); PG8_STAGE(PG8_SA(1, 0), cA + kstep, voffA); PG8_STAGE(PG8_SB(1, 1), cB + hstep + kstep, voffB);
;         PG8_WAIT_V(6); PG8_BAR;
.LBB0_230:
	s_lshl_b32 s26, s26, 5
	s_and_b32 s35, s26, 0x60
	s_add_i32 m0, s31, 0x18000
	v_lshl_add_u64 v[8:9], v[8:9], 0, s[14:15]
	s_lshl_b32 s34, s25, 13
	s_lshl_b32 s42, s35, 7
	global_load_lds_dwordx4 v[8:9], off
	v_lshl_add_u64 v[6:7], v[6:7], 0, s[14:15]
	s_add_i32 m0, s31, 0x1a000
	s_add_i32 s55, s31, 0x8000
	s_add_i32 s56, s31, 0xa000
	global_load_lds_dwordx4 v[6:7], off
	v_lshl_add_u64 v[2:3], v[2:3], 0, s[14:15]
	s_mov_b32 m0, s55
	s_add_u32 s26, s4, 0x40080
	global_load_lds_dwordx4 v[2:3], off
	v_lshl_add_u64 v[2:3], v[4:5], 0, s[14:15]
	s_mov_b32 m0, s56
	s_addc_u32 s27, s5, 0
	global_load_lds_dwordx4 v[2:3], off
	s_add_i32 m0, s31, 0x1c000
	v_lshl_add_u64 v[2:3], s[26:27], 0, v[176:177]
	global_load_lds_dwordx4 v[2:3], off
	v_lshl_add_u64 v[2:3], s[26:27], 0, v[140:141]
	s_add_i32 m0, s31, 0x1e000
	v_and_b32_e32 v1, 15, v10
	global_load_lds_dwordx4 v[2:3], off
	s_waitcnt vmcnt(8)
	s_barrier
	v_lshrrev_b32_e32 v2, 1, v10
	v_and_b32_e32 v2, 24, v2
	v_lshlrev_b32_e32 v3, 1, v2
	v_lshlrev_b32_e32 v4, 2, v1
	v_lshl_or_b32 v160, s25, 6, v1
	v_lshl_or_b32 v3, v1, 6, v3
	v_and_b32_e32 v1, 32, v4
	v_bitop3_b32 v5, v3, s34, v1 bitop3:0xde
	v_bitop3_b32 v161, v3, s42, v1 bitop3:0xde
	v_mov_b32_e32 v1, v177
	v_lshl_add_u64 v[142:143], s[22:23], 0, v[0:1]
	v_lshlrev_b32_e32 v0, 14, v11
	v_and_b32_e32 v0, 0xffff8000, v0
	v_lshl_add_u32 v0, v12, 11, v0
	v_and_b32_e32 v1, 1, v11
	v_lshl_or_b32 v0, v1, 6, v0
	s_add_i32 s25, 0, 0x20000
	v_lshl_add_u32 v144, v13, 1, v0
	v_lshlrev_b32_e32 v0, 14, v14
	s_cmpk_lt_u32 s24, 0x100
	v_and_b32_e32 v0, 0xffff8000, v0
	s_waitcnt vmcnt(6)
	s_cselect_b64 s[22:23], -1, 0
	s_and_b32 s24, s24, 0xffffff00
	v_lshl_add_u32 v0, v15, 11, v0
	v_and_b32_e32 v1, 1, v14
	v_lshl_add_u32 v162, v158, 2, s25
	s_add_i32 s25, s25, s24
	v_lshl_or_b32 v0, v1, 6, v0
	v_add_u32_e32 v163, s25, v4
	v_or_b32_e32 v164, s35, v2
	v_mov_b32_e32 v145, v177
	v_lshl_add_u32 v146, v16, 1, v0
	v_mov_b32_e32 v147, v177
	s_mov_b32 s58, 0
	v_add_u32_e32 v165, 0, v5
	s_barrier
	s_branch .LBB0_233
